# relaxed first-iteration waits in all six tiled GEMM instances plus SSD pipelined LDS reads
# baseline (speedup 1.0000x reference)
; #define PG8_STAGE(bufoff, gbase, voff) do { _Pragma("unroll") for (int _i = 0; _i < 2; ++_i) \
;         __builtin_amdgcn_global_load_lds((const unsigned*)((const char*)(gbase) + (voff)[_i]), (PG8_LAS unsigned*)(lds + (bufoff) + ldsw + _i * 8192), 16, 0, 0); } while (0)
; #define PG8_LDA(dst, b, h) do { _Pragma("unroll") for (int m = 0; m < 4; ++m) _Pragma("unroll") for (int k = 0; k < 2; ++k) dst[m][k] = *(const PG8_LAS bf16x8*)(lds + PG8_SA(b, h) + aoff + m * 2048 + k * 1024); } while (0)
; #define PG8_LDB(dst, b, h) do { _Pragma("unroll") for (int n = 0; n < 2; ++n) _Pragma("unroll") for (int k = 0; k < 2; ++k) dst[n][k] = *(const PG8_LAS bf16x8*)(lds + PG8_SB(b, h) + boff + n * 2048 + k * 1024); } while (0)
; #define PG8_MMA(ai, bj, At, Bt) do { __builtin_amdgcn_s_setprio(1); _Pragma("unroll") for (int m = 0; m < 4; ++m) _Pragma("unroll") for (int n = 0; n < 2; ++n) _Pragma("unroll") for (int k = 0; k < 2; ++k) \
;         acc[ai][bj][m][n] = __builtin_amdgcn_mfma_f32_16x16x32_bf16(Bt[n][k], At[m][k], acc[ai][bj][m][n], 0, 0, 0); __builtin_amdgcn_s_setprio(0); } while (0)
; #define PG8_WAIT_V(n) asm volatile("s_waitcnt vmcnt(" #n ")" ::: "memory")
; #define PG8_WAIT_L(n) asm volatile("s_waitcnt lgkmcnt(" #n ")" ::: "memory")
; #define PG8_BAR __builtin_amdgcn_s_barrier()
; template <class Epi, class Sched, bool ALIGN_EPI = false, bool SP2 = false>
; __device__ __forceinline__ void gemm_phase(PG8_LAS unsigned char* lds, const Gemm g, const Sched& S, const Epi& E, const int wave_id) {
;     ...
;             const char* a1 = cA + (size_t)(t + 1) * kstep;
;             const char* a2 = last ? nA : cA + (size_t)(t + 2) * kstep; const char* b2 = last ? nB : cB + (size_t)(t + 2) * kstep;
;             const char* a3 = a2 + kstep; const char* b3 = b2 + kstep;
;             if (last && has_next) S.a_ready(nxt);
;             if constexpr (SP2) {
;             PG8_LDB(B0, 0, 0); PG8_LDB(B1, 0, 1); PG8_SCHED; PG8_LDA(At, 0, 0); PG8_STAGE(PG8_SA(1, 1), a1 + hstepA, voffA);
;             PG8_WAIT_V(8); PG8_WAIT_L(0); PG8_BAR; PG8_MMA(0, 0, At, B0); PG8_MMA(0, 1, At, B1); PG8_BAR; PG8_SCHED;
;             PG8_LDA(At, 0, 1); PG8_STAGE(PG8_SB(0, 0), b2, voffB); PG8_STAGE(PG8_SB(0, 1), b2 + hstepB, voffB); PG8_STAGE(PG8_SA(0, 0), a2, voffA);
;             PG8_WAIT_V(8); PG8_WAIT_L(0); PG8_BAR; PG8_MMA(1, 0, At, B0); PG8_MMA(1, 1, At, B1); PG8_BAR; PG8_SCHED;
.LBB0_35:
	s_add_u32 s28, s26, 0xfff00080
	s_addc_u32 s29, s27, -1
	s_add_i32 s86, 0, 0x10000
	s_cmp_eq_u32 s83, 60
	s_cselect_b32 s31, s0, s29
	s_cselect_b32 s30, s1, s28
	v_add_u32_e32 v0, s86, v188
	s_cselect_b32 s29, s3, s38
	s_cselect_b32 s28, s19, s21
	s_add_i32 s91, 0, 0x14000
	ds_read_b128 v[130:133], v0
	ds_read_b128 v[134:137], v0 offset:1024
	ds_read_b128 v[138:141], v0 offset:2048
	ds_read_b128 v[142:145], v0 offset:3072
	v_add_u32_e32 v0, s91, v188
	ds_read_b128 v[146:149], v0
	ds_read_b128 v[150:153], v0 offset:1024
	ds_read_b128 v[166:169], v0 offset:2048
	ds_read_b128 v[178:181], v0 offset:3072
	v_lshl_add_u64 v[186:187], s[26:27], 0, v[162:163]
	s_add_i32 m0, s9, 0xc000
	ds_read_b128 v[182:185], v194
	ds_read_b128 v[196:199], v194 offset:1024
	ds_read_b128 v[200:203], v194 offset:2048
	ds_read_b128 v[204:207], v194 offset:3072
	ds_read_b128 v[208:211], v194 offset:4096
	ds_read_b128 v[212:215], v194 offset:5120
	ds_read_b128 v[216:219], v194 offset:6144
	ds_read_b128 v[220:223], v194 offset:7168
	global_load_lds_dwordx4 v[186:187], off
	v_lshl_add_u64 v[186:187], s[26:27], 0, v[164:165]
	s_add_i32 m0, s9, 0xe000
	s_nop 0
	global_load_lds_dwordx4 v[186:187], off
	s_waitcnt vmcnt(24)
	s_cmp_eq_u32 s98, 1
	s_cbranch_scc1 .Lrw_7
	s_waitcnt vmcnt(8)
.Lrw_7:
	s_waitcnt lgkmcnt(0)
	s_barrier
	s_setprio 1
	s_waitcnt lgkmcnt(0)
	v_mfma_f32_16x16x32_bf16 v[126:129], v[130:133], v[182:185], v[126:129]
	v_mfma_f32_16x16x32_bf16 v[122:125], v[138:141], v[182:185], v[122:125]
	v_mfma_f32_16x16x32_bf16 v[110:113], v[130:133], v[200:203], v[110:113]
	v_mfma_f32_16x16x32_bf16 v[106:109], v[138:141], v[200:203], v[106:109]
	v_mfma_f32_16x16x32_bf16 v[94:97], v[130:133], v[208:211], v[94:97]
	v_mfma_f32_16x16x32_bf16 v[90:93], v[138:141], v[208:211], v[90:93]
	v_mfma_f32_16x16x32_bf16 v[78:81], v[130:133], v[216:219], v[78:81]
	v_mfma_f32_16x16x32_bf16 v[74:77], v[138:141], v[216:219], v[74:77]
	v_mfma_f32_16x16x32_bf16 v[126:129], v[134:137], v[196:199], v[126:129]
	v_mfma_f32_16x16x32_bf16 v[122:125], v[142:145], v[196:199], v[122:125]
	v_mfma_f32_16x16x32_bf16 v[110:113], v[134:137], v[204:207], v[110:113]
	v_mfma_f32_16x16x32_bf16 v[106:109], v[142:145], v[204:207], v[106:109]
	v_mfma_f32_16x16x32_bf16 v[94:97], v[134:137], v[212:215], v[94:97]
	v_mfma_f32_16x16x32_bf16 v[90:93], v[142:145], v[212:215], v[90:93]
	v_mfma_f32_16x16x32_bf16 v[78:81], v[134:137], v[220:223], v[78:81]
	v_mfma_f32_16x16x32_bf16 v[74:77], v[142:145], v[220:223], v[74:77]
	s_setprio 0
	s_setprio 1
	v_mfma_f32_16x16x32_bf16 v[118:121], v[146:149], v[182:185], v[118:121]
	v_mfma_f32_16x16x32_bf16 v[114:117], v[166:169], v[182:185], v[114:117]
	v_mfma_f32_16x16x32_bf16 v[102:105], v[146:149], v[200:203], v[102:105]
	v_mfma_f32_16x16x32_bf16 v[98:101], v[166:169], v[200:203], v[98:101]
	v_mfma_f32_16x16x32_bf16 v[86:89], v[146:149], v[208:211], v[86:89]
	v_mfma_f32_16x16x32_bf16 v[82:85], v[166:169], v[208:211], v[82:85]
	v_mfma_f32_16x16x32_bf16 v[70:73], v[146:149], v[216:219], v[70:73]
	v_mfma_f32_16x16x32_bf16 v[66:69], v[166:169], v[216:219], v[66:69]
	v_mfma_f32_16x16x32_bf16 v[118:121], v[150:153], v[196:199], v[118:121]
	v_mfma_f32_16x16x32_bf16 v[114:117], v[178:181], v[196:199], v[114:117]
	v_mfma_f32_16x16x32_bf16 v[102:105], v[150:153], v[204:207], v[102:105]
	v_mfma_f32_16x16x32_bf16 v[98:101], v[178:181], v[204:207], v[98:101]
	v_mfma_f32_16x16x32_bf16 v[86:89], v[150:153], v[212:215], v[86:89]
	v_mfma_f32_16x16x32_bf16 v[82:85], v[178:181], v[212:215], v[82:85]
	v_mfma_f32_16x16x32_bf16 v[70:73], v[150:153], v[220:223], v[70:73]
	v_mfma_f32_16x16x32_bf16 v[66:69], v[178:181], v[220:223], v[66:69]
	s_setprio 0
	s_barrier
	s_add_i32 s86, s86, s14
	v_lshl_add_u64 v[186:187], s[28:29], 0, v[156:157]
	s_mov_b32 m0, s86
	ds_read_b128 v[182:185], v194 offset:16384
	ds_read_b128 v[196:199], v194 offset:17408
	ds_read_b128 v[200:203], v194 offset:18432
	ds_read_b128 v[204:207], v194 offset:19456
	ds_read_b128 v[208:211], v194 offset:20480
	ds_read_b128 v[212:215], v194 offset:21504
	ds_read_b128 v[216:219], v194 offset:22528
	ds_read_b128 v[220:223], v194 offset:23552
	global_load_lds_dwordx4 v[186:187], off
	s_add_i32 m0, s86, 0x2000
	s_add_u32 s86, s28, 0x100000
	v_lshl_add_u64 v[224:225], s[28:29], 0, v[160:161]
	s_addc_u32 s87, s29, 0
	s_add_i32 s91, s91, s14
	global_load_lds_dwordx4 v[224:225], off
	v_lshl_add_u64 v[234:235], s[86:87], 0, v[156:157]
	s_mov_b32 m0, s91
	v_lshl_add_u64 v[236:237], s[30:31], 0, v[158:159]
	global_load_lds_dwordx4 v[234:235], off
	v_lshl_add_u64 v[234:235], s[86:87], 0, v[160:161]
	s_add_i32 m0, s91, 0x2000
	s_nop 0
	global_load_lds_dwordx4 v[234:235], off
	v_lshl_add_u64 v[234:235], s[30:31], 0, v[154:155]
	s_mov_b32 m0, s9
	s_nop 0
	global_load_lds_dwordx4 v[234:235], off
	s_mov_b32 m0, s15
	s_nop 0
	global_load_lds_dwordx4 v[236:237], off
	s_waitcnt vmcnt(24)
	s_cmp_eq_u32 s98, 1
	s_cbranch_scc1 .Lrw_8
	s_waitcnt vmcnt(8)
; #define PG8_STAGE(bufoff, gbase, voff) do { _Pragma("unroll") for (int _i = 0; _i < 2; ++_i) \
;         __builtin_amdgcn_global_load_lds((const unsigned*)((const char*)(gbase) + (voff)[_i]), (PG8_LAS unsigned*)(lds + (bufoff) + ldsw + _i * 8192), 16, 0, 0); } while (0)
; #define PG8_LDA(dst, b, h) do { _Pragma("unroll") for (int m = 0; m < 4; ++m) _Pragma("unroll") for (int k = 0; k < 2; ++k) dst[m][k] = *(const PG8_LAS bf16x8*)(lds + PG8_SA(b, h) + aoff + m * 2048 + k * 1024); } while (0)
; #define PG8_LDB(dst, b, h) do { _Pragma("unroll") for (int n = 0; n < 2; ++n) _Pragma("unroll") for (int k = 0; k < 2; ++k) dst[n][k] = *(const PG8_LAS bf16x8*)(lds + PG8_SB(b, h) + boff + n * 2048 + k * 1024); } while (0)
; #define PG8_MMA(ai, bj, At, Bt) do { __builtin_amdgcn_s_setprio(1); _Pragma("unroll") for (int m = 0; m < 4; ++m) _Pragma("unroll") for (int n = 0; n < 2; ++n) _Pragma("unroll") for (int k = 0; k < 2; ++k) \
;         acc[ai][bj][m][n] = __builtin_amdgcn_mfma_f32_16x16x32_bf16(Bt[n][k], At[m][k], acc[ai][bj][m][n], 0, 0, 0); __builtin_amdgcn_s_setprio(0); } while (0)
; #define PG8_WAIT_V(n) asm volatile("s_waitcnt vmcnt(" #n ")" ::: "memory")
; #define PG8_WAIT_L(n) asm volatile("s_waitcnt lgkmcnt(" #n ")" ::: "memory")
; #define PG8_BAR __builtin_amdgcn_s_barrier()
; #define PG8_SCHED __builtin_amdgcn_sched_barrier(0)
; template <class Epi, class Sched, bool ALIGN_EPI = false, bool SP2 = false>
; __device__ __forceinline__ void gemm_phase(PG8_LAS unsigned char* lds, const Gemm g, const Sched& S, const Epi& E, const int wave_id) {
;     ...
;             PG8_WAIT_V(8); PG8_WAIT_L(0); PG8_BAR; PG8_MMA(1, 0, At, B0); PG8_MMA(1, 1, At, B1); PG8_BAR; PG8_SCHED;
;             PG8_LDB(B0, 1, 0); PG8_LDB(B1, 1, 1); PG8_SCHED; PG8_LDA(At, 1, 0); PG8_STAGE(PG8_SA(0, 1), a2 + hstepA, voffA);
;             PG8_WAIT_V(8); PG8_WAIT_L(0); PG8_BAR; PG8_MMA(0, 0, At, B0); PG8_MMA(0, 1, At, B1); PG8_BAR; PG8_SCHED;
.Lrw_8:
	s_mov_b32 s98, 0
	s_waitcnt lgkmcnt(0)
	s_barrier
	s_setprio 1
	s_waitcnt lgkmcnt(0)
	v_mfma_f32_16x16x32_bf16 v[62:65], v[130:133], v[182:185], v[62:65]
	v_mfma_f32_16x16x32_bf16 v[58:61], v[138:141], v[182:185], v[58:61]
	v_mfma_f32_16x16x32_bf16 v[46:49], v[130:133], v[200:203], v[46:49]
	v_mfma_f32_16x16x32_bf16 v[42:45], v[138:141], v[200:203], v[42:45]
	v_mfma_f32_16x16x32_bf16 v[30:33], v[130:133], v[208:211], v[30:33]
	v_mfma_f32_16x16x32_bf16 v[26:29], v[138:141], v[208:211], v[26:29]
	v_mfma_f32_16x16x32_bf16 v[14:17], v[130:133], v[216:219], v[14:17]
	v_mfma_f32_16x16x32_bf16 v[10:13], v[138:141], v[216:219], v[10:13]
	v_mfma_f32_16x16x32_bf16 v[62:65], v[134:137], v[196:199], v[62:65]
	v_mfma_f32_16x16x32_bf16 v[58:61], v[142:145], v[196:199], v[58:61]
	v_mfma_f32_16x16x32_bf16 v[46:49], v[134:137], v[204:207], v[46:49]
	v_mfma_f32_16x16x32_bf16 v[42:45], v[142:145], v[204:207], v[42:45]
	v_mfma_f32_16x16x32_bf16 v[30:33], v[134:137], v[212:215], v[30:33]
	v_mfma_f32_16x16x32_bf16 v[26:29], v[142:145], v[212:215], v[26:29]
	v_mfma_f32_16x16x32_bf16 v[14:17], v[134:137], v[220:223], v[14:17]
	v_mfma_f32_16x16x32_bf16 v[10:13], v[142:145], v[220:223], v[10:13]
	s_setprio 0
	s_setprio 1
	v_mfma_f32_16x16x32_bf16 v[54:57], v[146:149], v[182:185], v[54:57]
	v_mfma_f32_16x16x32_bf16 v[50:53], v[166:169], v[182:185], v[50:53]
	v_mfma_f32_16x16x32_bf16 v[38:41], v[146:149], v[200:203], v[38:41]
	v_mfma_f32_16x16x32_bf16 v[34:37], v[166:169], v[200:203], v[34:37]
	v_mfma_f32_16x16x32_bf16 v[22:25], v[146:149], v[208:211], v[22:25]
	v_mfma_f32_16x16x32_bf16 v[18:21], v[166:169], v[208:211], v[18:21]
	v_mfma_f32_16x16x32_bf16 v[6:9], v[146:149], v[216:219], v[6:9]
	v_mfma_f32_16x16x32_bf16 v[2:5], v[166:169], v[216:219], v[2:5]
	v_mfma_f32_16x16x32_bf16 v[54:57], v[150:153], v[196:199], v[54:57]
	v_mfma_f32_16x16x32_bf16 v[50:53], v[178:181], v[196:199], v[50:53]
	v_mfma_f32_16x16x32_bf16 v[38:41], v[150:153], v[204:207], v[38:41]
	v_mfma_f32_16x16x32_bf16 v[34:37], v[178:181], v[204:207], v[34:37]
	v_mfma_f32_16x16x32_bf16 v[22:25], v[150:153], v[212:215], v[22:25]
	v_mfma_f32_16x16x32_bf16 v[18:21], v[178:181], v[212:215], v[18:21]
	v_mfma_f32_16x16x32_bf16 v[6:9], v[150:153], v[220:223], v[6:9]
	v_mfma_f32_16x16x32_bf16 v[2:5], v[178:181], v[220:223], v[2:5]
	s_setprio 0
	s_barrier
	s_add_i32 s86, 0, 0x18000
	v_add_u32_e32 v0, s86, v188
	s_add_i32 s87, 0, 0x1c000
	ds_read_b128 v[130:133], v0
	ds_read_b128 v[134:137], v0 offset:1024
	ds_read_b128 v[138:141], v0 offset:2048
	ds_read_b128 v[142:145], v0 offset:3072
	v_add_u32_e32 v0, s87, v188
	ds_read_b128 v[146:149], v0
	ds_read_b128 v[150:153], v0 offset:1024
	ds_read_b128 v[166:169], v0 offset:2048
	ds_read_b128 v[178:181], v0 offset:3072
	s_add_u32 s30, s30, 0x100000
	s_addc_u32 s31, s31, 0
	s_mov_b32 m0, s34
	v_lshl_add_u64 v[240:241], s[30:31], 0, v[154:155]
	ds_read_b128 v[182:185], v194 offset:32768
	ds_read_b128 v[196:199], v194 offset:33792
	ds_read_b128 v[200:203], v194 offset:34816
	ds_read_b128 v[204:207], v194 offset:35840
	ds_read_b128 v[208:211], v194 offset:36864
	ds_read_b128 v[212:215], v194 offset:37888
	ds_read_b128 v[216:219], v194 offset:38912
	ds_read_b128 v[220:223], v194 offset:39936
	global_load_lds_dwordx4 v[240:241], off
	v_lshl_add_u64 v[240:241], s[30:31], 0, v[158:159]
	s_mov_b32 m0, s35
	s_nop 0
	global_load_lds_dwordx4 v[240:241], off
	s_waitcnt vmcnt(8)
	s_waitcnt lgkmcnt(0)
	s_barrier
	s_setprio 1
	s_waitcnt lgkmcnt(0)
	v_mfma_f32_16x16x32_bf16 v[126:129], v[130:133], v[182:185], v[126:129]
	v_mfma_f32_16x16x32_bf16 v[122:125], v[138:141], v[182:185], v[122:125]
	v_mfma_f32_16x16x32_bf16 v[110:113], v[130:133], v[200:203], v[110:113]
	v_mfma_f32_16x16x32_bf16 v[106:109], v[138:141], v[200:203], v[106:109]
	v_mfma_f32_16x16x32_bf16 v[94:97], v[130:133], v[208:211], v[94:97]
	v_mfma_f32_16x16x32_bf16 v[90:93], v[138:141], v[208:211], v[90:93]
	v_mfma_f32_16x16x32_bf16 v[78:81], v[130:133], v[216:219], v[78:81]
	v_mfma_f32_16x16x32_bf16 v[74:77], v[138:141], v[216:219], v[74:77]
	v_mfma_f32_16x16x32_bf16 v[126:129], v[134:137], v[196:199], v[126:129]
	v_mfma_f32_16x16x32_bf16 v[122:125], v[142:145], v[196:199], v[122:125]
	v_mfma_f32_16x16x32_bf16 v[110:113], v[134:137], v[204:207], v[110:113]
	v_mfma_f32_16x16x32_bf16 v[106:109], v[142:145], v[204:207], v[106:109]
	v_mfma_f32_16x16x32_bf16 v[94:97], v[134:137], v[212:215], v[94:97]
	v_mfma_f32_16x16x32_bf16 v[90:93], v[142:145], v[212:215], v[90:93]
	v_mfma_f32_16x16x32_bf16 v[78:81], v[134:137], v[220:223], v[78:81]
	v_mfma_f32_16x16x32_bf16 v[74:77], v[142:145], v[220:223], v[74:77]
	s_setprio 0
	s_setprio 1
	v_mfma_f32_16x16x32_bf16 v[118:121], v[146:149], v[182:185], v[118:121]
	v_mfma_f32_16x16x32_bf16 v[114:117], v[166:169], v[182:185], v[114:117]
	v_mfma_f32_16x16x32_bf16 v[102:105], v[146:149], v[200:203], v[102:105]
	v_mfma_f32_16x16x32_bf16 v[98:101], v[166:169], v[200:203], v[98:101]
	v_mfma_f32_16x16x32_bf16 v[86:89], v[146:149], v[208:211], v[86:89]
	v_mfma_f32_16x16x32_bf16 v[82:85], v[166:169], v[208:211], v[82:85]
	v_mfma_f32_16x16x32_bf16 v[70:73], v[146:149], v[216:219], v[70:73]
	v_mfma_f32_16x16x32_bf16 v[66:69], v[166:169], v[216:219], v[66:69]
	v_mfma_f32_16x16x32_bf16 v[118:121], v[150:153], v[196:199], v[118:121]
	v_mfma_f32_16x16x32_bf16 v[114:117], v[178:181], v[196:199], v[114:117]
	v_mfma_f32_16x16x32_bf16 v[102:105], v[150:153], v[204:207], v[102:105]
	v_mfma_f32_16x16x32_bf16 v[98:101], v[178:181], v[204:207], v[98:101]
	v_mfma_f32_16x16x32_bf16 v[86:89], v[150:153], v[212:215], v[86:89]
	v_mfma_f32_16x16x32_bf16 v[82:85], v[178:181], v[212:215], v[82:85]
	v_mfma_f32_16x16x32_bf16 v[70:73], v[150:153], v[220:223], v[70:73]
	v_mfma_f32_16x16x32_bf16 v[66:69], v[178:181], v[220:223], v[66:69]
	s_setprio 0
	s_barrier
; #define PG8_STAGE(bufoff, gbase, voff) do { _Pragma("unroll") for (int _i = 0; _i < 2; ++_i) \
;         __builtin_amdgcn_global_load_lds((const unsigned*)((const char*)(gbase) + (voff)[_i]), (PG8_LAS unsigned*)(lds + (bufoff) + ldsw + _i * 8192), 16, 0, 0); } while (0)
; #define PG8_LDA(dst, b, h) do { _Pragma("unroll") for (int m = 0; m < 4; ++m) _Pragma("unroll") for (int k = 0; k < 2; ++k) dst[m][k] = *(const PG8_LAS bf16x8*)(lds + PG8_SA(b, h) + aoff + m * 2048 + k * 1024); } while (0)
; #define PG8_MMA(ai, bj, At, Bt) do { __builtin_amdgcn_s_setprio(1); _Pragma("unroll") for (int m = 0; m < 4; ++m) _Pragma("unroll") for (int n = 0; n < 2; ++n) _Pragma("unroll") for (int k = 0; k < 2; ++k) \
;         acc[ai][bj][m][n] = __builtin_amdgcn_mfma_f32_16x16x32_bf16(Bt[n][k], At[m][k], acc[ai][bj][m][n], 0, 0, 0); __builtin_amdgcn_s_setprio(0); } while (0)
; #define PG8_WAIT_V(n) asm volatile("s_waitcnt vmcnt(" #n ")" ::: "memory")
; #define PG8_WAIT_L(n) asm volatile("s_waitcnt lgkmcnt(" #n ")" ::: "memory")
; #define PG8_BAR __builtin_amdgcn_s_barrier()
; #define PG8_SCHED __builtin_amdgcn_sched_barrier(0)
; template <class Epi, class Sched, bool ALIGN_EPI = false, bool SP2 = false>
; __device__ __forceinline__ void gemm_phase(PG8_LAS unsigned char* lds, const Gemm g, const Sched& S, const Epi& E, const int wave_id) {
;     ...
;         for (int t = 0; t < nt; t += 2) {
;             const bool last = (t == nt - 2);
;     ...
;             PG8_LDA(At, 1, 1); PG8_STAGE(PG8_SB(1, 0), b3, voffB); PG8_STAGE(PG8_SB(1, 1), b3 + hstepB, voffB); PG8_STAGE(PG8_SA(1, 0), a3, voffA);
;             PG8_WAIT_V(8); PG8_WAIT_L(0); PG8_BAR; PG8_MMA(1, 0, At, B0); PG8_MMA(1, 1, At, B1); PG8_BAR; PG8_SCHED;
	s_add_i32 s30, s86, s14
	v_lshl_add_u64 v[186:187], v[186:187], 0, s[62:63]
	s_mov_b32 m0, s30
	ds_read_b128 v[182:185], v194 offset:49152
	ds_read_b128 v[196:199], v194 offset:50176
	ds_read_b128 v[200:203], v194 offset:51200
	ds_read_b128 v[204:207], v194 offset:52224
	ds_read_b128 v[208:211], v194 offset:53248
	ds_read_b128 v[212:215], v194 offset:54272
	ds_read_b128 v[216:219], v194 offset:55296
	ds_read_b128 v[220:223], v194 offset:56320
	global_load_lds_dwordx4 v[186:187], off
	s_add_i32 m0, s30, 0x2000
	s_add_u32 s28, s28, 0x100080
	v_lshl_add_u64 v[186:187], v[224:225], 0, s[62:63]
	s_addc_u32 s29, s29, 0
	s_add_i32 s30, s87, s14
	global_load_lds_dwordx4 v[186:187], off
	v_lshl_add_u64 v[186:187], s[28:29], 0, v[156:157]
	s_mov_b32 m0, s30
	s_nop 0
	global_load_lds_dwordx4 v[186:187], off
	v_lshl_add_u64 v[186:187], s[28:29], 0, v[160:161]
	s_add_i32 m0, s30, 0x2000
	s_nop 0
	global_load_lds_dwordx4 v[186:187], off
	v_lshl_add_u64 v[186:187], v[234:235], 0, s[62:63]
	s_mov_b32 m0, s50
	s_nop 0
	global_load_lds_dwordx4 v[186:187], off
	v_lshl_add_u64 v[186:187], v[236:237], 0, s[62:63]
	s_mov_b32 m0, s76
	s_nop 0
	global_load_lds_dwordx4 v[186:187], off
	s_waitcnt vmcnt(8)
	s_waitcnt lgkmcnt(0)
	s_barrier
	s_setprio 1
	s_waitcnt lgkmcnt(0)
	v_mfma_f32_16x16x32_bf16 v[62:65], v[130:133], v[182:185], v[62:65]
	v_mfma_f32_16x16x32_bf16 v[58:61], v[138:141], v[182:185], v[58:61]
	v_mfma_f32_16x16x32_bf16 v[46:49], v[130:133], v[200:203], v[46:49]
	v_mfma_f32_16x16x32_bf16 v[42:45], v[138:141], v[200:203], v[42:45]
	v_mfma_f32_16x16x32_bf16 v[30:33], v[130:133], v[208:211], v[30:33]
	v_mfma_f32_16x16x32_bf16 v[26:29], v[138:141], v[208:211], v[26:29]
	v_mfma_f32_16x16x32_bf16 v[14:17], v[130:133], v[216:219], v[14:17]
	v_mfma_f32_16x16x32_bf16 v[10:13], v[138:141], v[216:219], v[10:13]
	v_mfma_f32_16x16x32_bf16 v[62:65], v[134:137], v[196:199], v[62:65]
	v_mfma_f32_16x16x32_bf16 v[58:61], v[142:145], v[196:199], v[58:61]
	v_mfma_f32_16x16x32_bf16 v[46:49], v[134:137], v[204:207], v[46:49]
	v_mfma_f32_16x16x32_bf16 v[42:45], v[142:145], v[204:207], v[42:45]
	v_mfma_f32_16x16x32_bf16 v[30:33], v[134:137], v[212:215], v[30:33]
	v_mfma_f32_16x16x32_bf16 v[26:29], v[142:145], v[212:215], v[26:29]
	v_mfma_f32_16x16x32_bf16 v[14:17], v[134:137], v[220:223], v[14:17]
	v_mfma_f32_16x16x32_bf16 v[10:13], v[142:145], v[220:223], v[10:13]
	s_setprio 0
	s_setprio 1
	v_mfma_f32_16x16x32_bf16 v[54:57], v[146:149], v[182:185], v[54:57]
	v_mfma_f32_16x16x32_bf16 v[50:53], v[166:169], v[182:185], v[50:53]
	v_mfma_f32_16x16x32_bf16 v[38:41], v[146:149], v[200:203], v[38:41]
	v_mfma_f32_16x16x32_bf16 v[34:37], v[166:169], v[200:203], v[34:37]
	v_mfma_f32_16x16x32_bf16 v[22:25], v[146:149], v[208:211], v[22:25]
	v_mfma_f32_16x16x32_bf16 v[18:21], v[166:169], v[208:211], v[18:21]
	v_mfma_f32_16x16x32_bf16 v[6:9], v[146:149], v[216:219], v[6:9]
	v_mfma_f32_16x16x32_bf16 v[2:5], v[166:169], v[216:219], v[2:5]
	v_mfma_f32_16x16x32_bf16 v[54:57], v[150:153], v[196:199], v[54:57]
	v_mfma_f32_16x16x32_bf16 v[50:53], v[178:181], v[196:199], v[50:53]
	v_mfma_f32_16x16x32_bf16 v[38:41], v[150:153], v[204:207], v[38:41]
	v_mfma_f32_16x16x32_bf16 v[34:37], v[178:181], v[204:207], v[34:37]
	v_mfma_f32_16x16x32_bf16 v[22:25], v[150:153], v[212:215], v[22:25]
	v_mfma_f32_16x16x32_bf16 v[18:21], v[178:181], v[212:215], v[18:21]
	v_mfma_f32_16x16x32_bf16 v[6:9], v[150:153], v[220:223], v[6:9]
	v_mfma_f32_16x16x32_bf16 v[2:5], v[178:181], v[220:223], v[2:5]
	s_setprio 0
	s_barrier
	s_add_i32 s83, s83, 2
	s_add_u32 s26, s26, 0x100
	s_addc_u32 s27, s27, 0
	s_add_u32 s21, s21, 0x100
	s_addc_u32 s38, s38, 0
	s_cmp_gt_u32 s83, 61
	s_cbranch_scc0 .LBB0_35
	s_and_b64 vcc, exec, s[16:17]
	s_cbranch_vccz .LBB0_38
	s_barrier

; #define PG8_BAR __builtin_amdgcn_s_barrier()
; template <class Epi, class Sched, bool ALIGN_EPI = false, bool SP2 = false>
; __device__ __forceinline__ void gemm_phase(PG8_LAS unsigned char* lds, const Gemm g, const Sched& S, const Epi& E, const int wave_id) {
;     ...
;         if constexpr (ALIGN_EPI) { if (wr == 0) PG8_BAR; }
;         if constexpr (!Epi::AFTER_DRAIN) { E(acc, cur, wr, wc, fr, fq); S.done(cur); }
;         if (!has_next) break;
; #pragma unroll
;         for (int a = 0; a < 2; ++a)
; #pragma unroll
;             for (int b = 0; b < 2; ++b)
; #pragma unroll
;                 for (int m = 0; m < 4; ++m)
; #pragma unroll
;                     for (int n = 0; n < 2; ++n) acc[a][b][m][n] = (f32x4){0.f, 0.f, 0.f, 0.f};
;         cur = nxt; cA = nA; cB = nB; ++ui;
;         if constexpr (Epi::HAS_PF) E.prefetch(cur, tid);
;         if constexpr (ALIGN_EPI) { if (wr == 1) PG8_BAR; }
.LBB0_58:
	s_or_b64 exec, exec, s[26:27]
	s_andn2_b64 vcc, exec, s[6:7]
	s_mov_b64 s[2:3], -1
	s_cbranch_vccnz .LBB0_27
	s_mov_b32 s98, 1
	s_andn2_b64 vcc, exec, s[10:11]
	s_cbranch_vccnz .LBB0_26
	s_barrier
	s_branch .LBB0_26

; #define PG8_STAGE(bufoff, gbase, voff) do { _Pragma("unroll") for (int _i = 0; _i < 2; ++_i) \
;         __builtin_amdgcn_global_load_lds((const unsigned*)((const char*)(gbase) + (voff)[_i]), (PG8_LAS unsigned*)(lds + (bufoff) + ldsw + _i * 8192), 16, 0, 0); } while (0)
; #define PG8_LDA(dst, b, h) do { _Pragma("unroll") for (int m = 0; m < 4; ++m) _Pragma("unroll") for (int k = 0; k < 2; ++k) dst[m][k] = *(const PG8_LAS bf16x8*)(lds + PG8_SA(b, h) + aoff + m * 2048 + k * 1024); } while (0)
; #define PG8_LDB(dst, b, h) do { _Pragma("unroll") for (int n = 0; n < 2; ++n) _Pragma("unroll") for (int k = 0; k < 2; ++k) dst[n][k] = *(const PG8_LAS bf16x8*)(lds + PG8_SB(b, h) + boff + n * 2048 + k * 1024); } while (0)
; #define PG8_MMA(ai, bj, At, Bt) do { __builtin_amdgcn_s_setprio(1); _Pragma("unroll") for (int m = 0; m < 4; ++m) _Pragma("unroll") for (int n = 0; n < 2; ++n) _Pragma("unroll") for (int k = 0; k < 2; ++k) \
;         acc[ai][bj][m][n] = __builtin_amdgcn_mfma_f32_16x16x32_bf16(Bt[n][k], At[m][k], acc[ai][bj][m][n], 0, 0, 0); __builtin_amdgcn_s_setprio(0); } while (0)
; #define PG8_WAIT_V(n) asm volatile("s_waitcnt vmcnt(" #n ")" ::: "memory")
; #define PG8_WAIT_L(n) asm volatile("s_waitcnt lgkmcnt(" #n ")" ::: "memory")
; #define PG8_BAR __builtin_amdgcn_s_barrier()
; template <class Epi, class Sched, bool ALIGN_EPI = false, bool SP2 = false>
; __device__ __forceinline__ void gemm_phase(PG8_LAS unsigned char* lds, const Gemm g, const Sched& S, const Epi& E, const int wave_id) {
;     ...
;             const char* a1 = cA + (size_t)(t + 1) * kstep;
;             const char* a2 = last ? nA : cA + (size_t)(t + 2) * kstep; const char* b2 = last ? nB : cB + (size_t)(t + 2) * kstep;
;             const char* a3 = a2 + kstep; const char* b3 = b2 + kstep;
;             if (last && has_next) S.a_ready(nxt);
;             if constexpr (SP2) {
;             PG8_LDB(B0, 0, 0); PG8_LDB(B1, 0, 1); PG8_SCHED; PG8_LDA(At, 0, 0); PG8_STAGE(PG8_SA(1, 1), a1 + hstepA, voffA);
;             PG8_WAIT_V(8); PG8_WAIT_L(0); PG8_BAR; PG8_MMA(0, 0, At, B0); PG8_MMA(0, 1, At, B1); PG8_BAR; PG8_SCHED;
;             PG8_LDA(At, 0, 1); PG8_STAGE(PG8_SB(0, 0), b2, voffB); PG8_STAGE(PG8_SB(0, 1), b2 + hstepB, voffB); PG8_STAGE(PG8_SA(0, 0), a2, voffA);
;             PG8_WAIT_V(8); PG8_WAIT_L(0); PG8_BAR; PG8_MMA(1, 0, At, B0); PG8_MMA(1, 1, At, B1); PG8_BAR; PG8_SCHED;
.LBB0_189:
	s_add_u32 s10, s12, 0x100
	s_addc_u32 s11, s13, 0
	s_add_i32 s39, 0, 0x10000
	s_cmp_eq_u32 vcc_lo, 28
	s_cselect_b32 s31, s25, s11
	s_cselect_b32 s30, s24, s10
	v_add_u32_e32 v0, s39, v206
	s_cselect_b32 s29, s23, s91
	s_cselect_b32 s28, s87, s38
	s_add_i32 vcc_hi, 0, 0x14000
	ds_read_b128 v[122:125], v0
	ds_read_b128 v[134:137], v0 offset:1024
	ds_read_b128 v[138:141], v0 offset:2048
	ds_read_b128 v[142:145], v0 offset:3072
	v_add_u32_e32 v0, vcc_hi, v206
	ds_read_b128 v[146:149], v0
	ds_read_b128 v[150:153], v0 offset:1024
	ds_read_b128 v[154:157], v0 offset:2048
	ds_read_b128 v[158:161], v0 offset:3072
	v_lshl_add_u64 v[222:223], s[12:13], 0, v[178:179]
	s_add_i32 m0, s17, 0xc000
	ds_read_b128 v[182:185], v212
	ds_read_b128 v[186:189], v212 offset:1024
	ds_read_b128 v[190:193], v212 offset:2048
	ds_read_b128 v[194:197], v212 offset:3072
	ds_read_b128 v[198:201], v212 offset:4096
	ds_read_b128 v[202:205], v212 offset:5120
	ds_read_b128 v[214:217], v212 offset:6144
	ds_read_b128 v[218:221], v212 offset:7168
	global_load_lds_dwordx4 v[222:223], off
	v_lshl_add_u64 v[222:223], s[12:13], 0, v[180:181]
	s_add_i32 m0, s17, 0xe000
	s_nop 0
	global_load_lds_dwordx4 v[222:223], off
	s_waitcnt vmcnt(24)
	s_cmp_eq_u32 s98, 1
	s_cbranch_scc1 .Lrw_9
	s_waitcnt vmcnt(8)
.Lrw_9:
	s_waitcnt lgkmcnt(0)
	s_barrier
	s_setprio 1
	s_waitcnt lgkmcnt(0)
	v_mfma_f32_16x16x32_bf16 v[130:133], v[122:125], v[182:185], v[130:133]
	v_mfma_f32_16x16x32_bf16 v[126:129], v[138:141], v[182:185], v[126:129]
	v_mfma_f32_16x16x32_bf16 v[110:113], v[122:125], v[190:193], v[110:113]
	v_mfma_f32_16x16x32_bf16 v[106:109], v[138:141], v[190:193], v[106:109]
	v_mfma_f32_16x16x32_bf16 v[94:97], v[122:125], v[198:201], v[94:97]
	v_mfma_f32_16x16x32_bf16 v[90:93], v[138:141], v[198:201], v[90:93]
	v_mfma_f32_16x16x32_bf16 v[78:81], v[122:125], v[214:217], v[78:81]
	v_mfma_f32_16x16x32_bf16 v[74:77], v[138:141], v[214:217], v[74:77]
	v_mfma_f32_16x16x32_bf16 v[130:133], v[134:137], v[186:189], v[130:133]
	v_mfma_f32_16x16x32_bf16 v[126:129], v[142:145], v[186:189], v[126:129]
	v_mfma_f32_16x16x32_bf16 v[110:113], v[134:137], v[194:197], v[110:113]
	v_mfma_f32_16x16x32_bf16 v[106:109], v[142:145], v[194:197], v[106:109]
	v_mfma_f32_16x16x32_bf16 v[94:97], v[134:137], v[202:205], v[94:97]
	v_mfma_f32_16x16x32_bf16 v[90:93], v[142:145], v[202:205], v[90:93]
	v_mfma_f32_16x16x32_bf16 v[78:81], v[134:137], v[218:221], v[78:81]
	v_mfma_f32_16x16x32_bf16 v[74:77], v[142:145], v[218:221], v[74:77]
	s_setprio 0
	s_setprio 1
	v_mfma_f32_16x16x32_bf16 v[118:121], v[146:149], v[182:185], v[118:121]
	v_mfma_f32_16x16x32_bf16 v[114:117], v[154:157], v[182:185], v[114:117]
	v_mfma_f32_16x16x32_bf16 v[102:105], v[146:149], v[190:193], v[102:105]
	v_mfma_f32_16x16x32_bf16 v[98:101], v[154:157], v[190:193], v[98:101]
	v_mfma_f32_16x16x32_bf16 v[86:89], v[146:149], v[198:201], v[86:89]
	v_mfma_f32_16x16x32_bf16 v[82:85], v[154:157], v[198:201], v[82:85]
	v_mfma_f32_16x16x32_bf16 v[70:73], v[146:149], v[214:217], v[70:73]
	v_mfma_f32_16x16x32_bf16 v[66:69], v[154:157], v[214:217], v[66:69]
	v_mfma_f32_16x16x32_bf16 v[118:121], v[150:153], v[186:189], v[118:121]
	v_mfma_f32_16x16x32_bf16 v[114:117], v[158:161], v[186:189], v[114:117]
	v_mfma_f32_16x16x32_bf16 v[102:105], v[150:153], v[194:197], v[102:105]
	v_mfma_f32_16x16x32_bf16 v[98:101], v[158:161], v[194:197], v[98:101]
	v_mfma_f32_16x16x32_bf16 v[86:89], v[150:153], v[202:205], v[86:89]
	v_mfma_f32_16x16x32_bf16 v[82:85], v[158:161], v[202:205], v[82:85]
	v_mfma_f32_16x16x32_bf16 v[70:73], v[150:153], v[218:221], v[70:73]
	v_mfma_f32_16x16x32_bf16 v[66:69], v[158:161], v[218:221], v[66:69]
	s_setprio 0
	s_barrier
	s_add_i32 s12, s39, s35
	v_lshl_add_u64 v[222:223], s[28:29], 0, v[164:165]
	s_mov_b32 m0, s12
	ds_read_b128 v[182:185], v212 offset:16384
	ds_read_b128 v[186:189], v212 offset:17408
	ds_read_b128 v[190:193], v212 offset:18432
	ds_read_b128 v[194:197], v212 offset:19456
	ds_read_b128 v[198:201], v212 offset:20480
	ds_read_b128 v[202:205], v212 offset:21504
	ds_read_b128 v[214:217], v212 offset:22528
	ds_read_b128 v[218:221], v212 offset:23552
	global_load_lds_dwordx4 v[222:223], off
	s_add_i32 m0, s12, 0x2000
	s_add_u32 s12, s28, 0x80000
	v_lshl_add_u64 v[224:225], s[28:29], 0, v[168:169]
	s_addc_u32 s13, s29, 0
	s_add_i32 s39, vcc_hi, s35
	global_load_lds_dwordx4 v[224:225], off
	v_lshl_add_u64 v[234:235], s[12:13], 0, v[164:165]
	s_mov_b32 m0, s39
	v_lshl_add_u64 v[236:237], s[30:31], 0, v[166:167]
	global_load_lds_dwordx4 v[234:235], off
	v_lshl_add_u64 v[234:235], s[12:13], 0, v[168:169]
	s_add_i32 m0, s39, 0x2000
	s_nop 0
	global_load_lds_dwordx4 v[234:235], off
	v_lshl_add_u64 v[234:235], s[30:31], 0, v[162:163]
	s_mov_b32 m0, s17
	s_nop 0
	global_load_lds_dwordx4 v[234:235], off
	s_mov_b32 m0, s36
	s_nop 0
	global_load_lds_dwordx4 v[236:237], off
	s_waitcnt vmcnt(24)
	s_cmp_eq_u32 s98, 1
	s_cbranch_scc1 .Lrw_10
	s_waitcnt vmcnt(8)
; #define PG8_STAGE(bufoff, gbase, voff) do { _Pragma("unroll") for (int _i = 0; _i < 2; ++_i) \
;         __builtin_amdgcn_global_load_lds((const unsigned*)((const char*)(gbase) + (voff)[_i]), (PG8_LAS unsigned*)(lds + (bufoff) + ldsw + _i * 8192), 16, 0, 0); } while (0)
; #define PG8_LDA(dst, b, h) do { _Pragma("unroll") for (int m = 0; m < 4; ++m) _Pragma("unroll") for (int k = 0; k < 2; ++k) dst[m][k] = *(const PG8_LAS bf16x8*)(lds + PG8_SA(b, h) + aoff + m * 2048 + k * 1024); } while (0)
; #define PG8_LDB(dst, b, h) do { _Pragma("unroll") for (int n = 0; n < 2; ++n) _Pragma("unroll") for (int k = 0; k < 2; ++k) dst[n][k] = *(const PG8_LAS bf16x8*)(lds + PG8_SB(b, h) + boff + n * 2048 + k * 1024); } while (0)
; #define PG8_MMA(ai, bj, At, Bt) do { __builtin_amdgcn_s_setprio(1); _Pragma("unroll") for (int m = 0; m < 4; ++m) _Pragma("unroll") for (int n = 0; n < 2; ++n) _Pragma("unroll") for (int k = 0; k < 2; ++k) \
;         acc[ai][bj][m][n] = __builtin_amdgcn_mfma_f32_16x16x32_bf16(Bt[n][k], At[m][k], acc[ai][bj][m][n], 0, 0, 0); __builtin_amdgcn_s_setprio(0); } while (0)
; #define PG8_WAIT_V(n) asm volatile("s_waitcnt vmcnt(" #n ")" ::: "memory")
; #define PG8_WAIT_L(n) asm volatile("s_waitcnt lgkmcnt(" #n ")" ::: "memory")
; #define PG8_BAR __builtin_amdgcn_s_barrier()
; #define PG8_SCHED __builtin_amdgcn_sched_barrier(0)
; template <class Epi, class Sched, bool ALIGN_EPI = false, bool SP2 = false>
; __device__ __forceinline__ void gemm_phase(PG8_LAS unsigned char* lds, const Gemm g, const Sched& S, const Epi& E, const int wave_id) {
;     ...
;             PG8_WAIT_V(8); PG8_WAIT_L(0); PG8_BAR; PG8_MMA(1, 0, At, B0); PG8_MMA(1, 1, At, B1); PG8_BAR; PG8_SCHED;
;             PG8_LDB(B0, 1, 0); PG8_LDB(B1, 1, 1); PG8_SCHED; PG8_LDA(At, 1, 0); PG8_STAGE(PG8_SA(0, 1), a2 + hstepA, voffA);
;             PG8_WAIT_V(8); PG8_WAIT_L(0); PG8_BAR; PG8_MMA(0, 0, At, B0); PG8_MMA(0, 1, At, B1); PG8_BAR; PG8_SCHED;
.Lrw_10:
	s_mov_b32 s98, 0
	s_waitcnt lgkmcnt(0)
	s_barrier
	s_setprio 1
	s_waitcnt lgkmcnt(0)
	v_mfma_f32_16x16x32_bf16 v[62:65], v[122:125], v[182:185], v[62:65]
	v_mfma_f32_16x16x32_bf16 v[58:61], v[138:141], v[182:185], v[58:61]
	v_mfma_f32_16x16x32_bf16 v[46:49], v[122:125], v[190:193], v[46:49]
	v_mfma_f32_16x16x32_bf16 v[42:45], v[138:141], v[190:193], v[42:45]
	v_mfma_f32_16x16x32_bf16 v[30:33], v[122:125], v[198:201], v[30:33]
	v_mfma_f32_16x16x32_bf16 v[26:29], v[138:141], v[198:201], v[26:29]
	v_mfma_f32_16x16x32_bf16 v[14:17], v[122:125], v[214:217], v[14:17]
	v_mfma_f32_16x16x32_bf16 v[10:13], v[138:141], v[214:217], v[10:13]
	v_mfma_f32_16x16x32_bf16 v[62:65], v[134:137], v[186:189], v[62:65]
	v_mfma_f32_16x16x32_bf16 v[58:61], v[142:145], v[186:189], v[58:61]
	v_mfma_f32_16x16x32_bf16 v[46:49], v[134:137], v[194:197], v[46:49]
	v_mfma_f32_16x16x32_bf16 v[42:45], v[142:145], v[194:197], v[42:45]
	v_mfma_f32_16x16x32_bf16 v[30:33], v[134:137], v[202:205], v[30:33]
	v_mfma_f32_16x16x32_bf16 v[26:29], v[142:145], v[202:205], v[26:29]
	v_mfma_f32_16x16x32_bf16 v[14:17], v[134:137], v[218:221], v[14:17]
	v_mfma_f32_16x16x32_bf16 v[10:13], v[142:145], v[218:221], v[10:13]
	s_setprio 0
	s_setprio 1
	v_mfma_f32_16x16x32_bf16 v[54:57], v[146:149], v[182:185], v[54:57]
	v_mfma_f32_16x16x32_bf16 v[50:53], v[154:157], v[182:185], v[50:53]
	v_mfma_f32_16x16x32_bf16 v[38:41], v[146:149], v[190:193], v[38:41]
	v_mfma_f32_16x16x32_bf16 v[34:37], v[154:157], v[190:193], v[34:37]
	v_mfma_f32_16x16x32_bf16 v[22:25], v[146:149], v[198:201], v[22:25]
	v_mfma_f32_16x16x32_bf16 v[18:21], v[154:157], v[198:201], v[18:21]
	v_mfma_f32_16x16x32_bf16 v[6:9], v[146:149], v[214:217], v[6:9]
	v_mfma_f32_16x16x32_bf16 v[2:5], v[154:157], v[214:217], v[2:5]
	v_mfma_f32_16x16x32_bf16 v[54:57], v[150:153], v[186:189], v[54:57]
	v_mfma_f32_16x16x32_bf16 v[50:53], v[158:161], v[186:189], v[50:53]
	v_mfma_f32_16x16x32_bf16 v[38:41], v[150:153], v[194:197], v[38:41]
	v_mfma_f32_16x16x32_bf16 v[34:37], v[158:161], v[194:197], v[34:37]
	v_mfma_f32_16x16x32_bf16 v[22:25], v[150:153], v[202:205], v[22:25]
	v_mfma_f32_16x16x32_bf16 v[18:21], v[158:161], v[202:205], v[18:21]
	v_mfma_f32_16x16x32_bf16 v[6:9], v[150:153], v[218:221], v[6:9]
	v_mfma_f32_16x16x32_bf16 v[2:5], v[158:161], v[218:221], v[2:5]
	s_setprio 0
	s_barrier
	s_add_i32 s39, 0, 0x18000
	v_add_u32_e32 v0, s39, v206
	s_add_i32 vcc_hi, 0, 0x1c000
	ds_read_b128 v[122:125], v0
	ds_read_b128 v[134:137], v0 offset:1024
	ds_read_b128 v[138:141], v0 offset:2048
	ds_read_b128 v[142:145], v0 offset:3072
	v_add_u32_e32 v0, vcc_hi, v206
	ds_read_b128 v[146:149], v0
	ds_read_b128 v[150:153], v0 offset:1024
	ds_read_b128 v[154:157], v0 offset:2048
	ds_read_b128 v[158:161], v0 offset:3072
	s_add_u32 s12, s30, 0x180000
	s_addc_u32 s13, s31, 0
	s_mov_b32 m0, s37
	v_lshl_add_u64 v[240:241], s[12:13], 0, v[162:163]
	ds_read_b128 v[182:185], v212 offset:32768
	ds_read_b128 v[186:189], v212 offset:33792
	ds_read_b128 v[190:193], v212 offset:34816
	ds_read_b128 v[194:197], v212 offset:35840
	ds_read_b128 v[198:201], v212 offset:36864
	ds_read_b128 v[202:205], v212 offset:37888
	ds_read_b128 v[214:217], v212 offset:38912
	ds_read_b128 v[218:221], v212 offset:39936
	global_load_lds_dwordx4 v[240:241], off
	v_lshl_add_u64 v[240:241], s[12:13], 0, v[166:167]
	s_mov_b32 m0, s76
	s_nop 0
	global_load_lds_dwordx4 v[240:241], off
	s_waitcnt vmcnt(8)
	s_waitcnt lgkmcnt(0)
	s_barrier
	s_setprio 1
	s_waitcnt lgkmcnt(0)
	v_mfma_f32_16x16x32_bf16 v[130:133], v[122:125], v[182:185], v[130:133]
	v_mfma_f32_16x16x32_bf16 v[126:129], v[138:141], v[182:185], v[126:129]
	v_mfma_f32_16x16x32_bf16 v[110:113], v[122:125], v[190:193], v[110:113]
	v_mfma_f32_16x16x32_bf16 v[106:109], v[138:141], v[190:193], v[106:109]
	v_mfma_f32_16x16x32_bf16 v[94:97], v[122:125], v[198:201], v[94:97]
	v_mfma_f32_16x16x32_bf16 v[90:93], v[138:141], v[198:201], v[90:93]
	v_mfma_f32_16x16x32_bf16 v[78:81], v[122:125], v[214:217], v[78:81]
	v_mfma_f32_16x16x32_bf16 v[74:77], v[138:141], v[214:217], v[74:77]
	v_mfma_f32_16x16x32_bf16 v[130:133], v[134:137], v[186:189], v[130:133]
	v_mfma_f32_16x16x32_bf16 v[126:129], v[142:145], v[186:189], v[126:129]
	v_mfma_f32_16x16x32_bf16 v[110:113], v[134:137], v[194:197], v[110:113]
	v_mfma_f32_16x16x32_bf16 v[106:109], v[142:145], v[194:197], v[106:109]
	v_mfma_f32_16x16x32_bf16 v[94:97], v[134:137], v[202:205], v[94:97]
	v_mfma_f32_16x16x32_bf16 v[90:93], v[142:145], v[202:205], v[90:93]
	v_mfma_f32_16x16x32_bf16 v[78:81], v[134:137], v[218:221], v[78:81]
	v_mfma_f32_16x16x32_bf16 v[74:77], v[142:145], v[218:221], v[74:77]
	s_setprio 0
	s_setprio 1
	v_mfma_f32_16x16x32_bf16 v[118:121], v[146:149], v[182:185], v[118:121]
	v_mfma_f32_16x16x32_bf16 v[114:117], v[154:157], v[182:185], v[114:117]
	v_mfma_f32_16x16x32_bf16 v[102:105], v[146:149], v[190:193], v[102:105]
	v_mfma_f32_16x16x32_bf16 v[98:101], v[154:157], v[190:193], v[98:101]
	v_mfma_f32_16x16x32_bf16 v[86:89], v[146:149], v[198:201], v[86:89]
	v_mfma_f32_16x16x32_bf16 v[82:85], v[154:157], v[198:201], v[82:85]
	v_mfma_f32_16x16x32_bf16 v[70:73], v[146:149], v[214:217], v[70:73]
	v_mfma_f32_16x16x32_bf16 v[66:69], v[154:157], v[214:217], v[66:69]
	v_mfma_f32_16x16x32_bf16 v[118:121], v[150:153], v[186:189], v[118:121]
	v_mfma_f32_16x16x32_bf16 v[114:117], v[158:161], v[186:189], v[114:117]
	v_mfma_f32_16x16x32_bf16 v[102:105], v[150:153], v[194:197], v[102:105]
	v_mfma_f32_16x16x32_bf16 v[98:101], v[158:161], v[194:197], v[98:101]
	v_mfma_f32_16x16x32_bf16 v[86:89], v[150:153], v[202:205], v[86:89]
	v_mfma_f32_16x16x32_bf16 v[82:85], v[158:161], v[202:205], v[82:85]
	v_mfma_f32_16x16x32_bf16 v[70:73], v[150:153], v[218:221], v[70:73]
	v_mfma_f32_16x16x32_bf16 v[66:69], v[158:161], v[218:221], v[66:69]
	s_setprio 0
	s_barrier
; #define PG8_STAGE(bufoff, gbase, voff) do { _Pragma("unroll") for (int _i = 0; _i < 2; ++_i) \
;         __builtin_amdgcn_global_load_lds((const unsigned*)((const char*)(gbase) + (voff)[_i]), (PG8_LAS unsigned*)(lds + (bufoff) + ldsw + _i * 8192), 16, 0, 0); } while (0)
; #define PG8_LDA(dst, b, h) do { _Pragma("unroll") for (int m = 0; m < 4; ++m) _Pragma("unroll") for (int k = 0; k < 2; ++k) dst[m][k] = *(const PG8_LAS bf16x8*)(lds + PG8_SA(b, h) + aoff + m * 2048 + k * 1024); } while (0)
; #define PG8_MMA(ai, bj, At, Bt) do { __builtin_amdgcn_s_setprio(1); _Pragma("unroll") for (int m = 0; m < 4; ++m) _Pragma("unroll") for (int n = 0; n < 2; ++n) _Pragma("unroll") for (int k = 0; k < 2; ++k) \
;         acc[ai][bj][m][n] = __builtin_amdgcn_mfma_f32_16x16x32_bf16(Bt[n][k], At[m][k], acc[ai][bj][m][n], 0, 0, 0); __builtin_amdgcn_s_setprio(0); } while (0)
; #define PG8_WAIT_V(n) asm volatile("s_waitcnt vmcnt(" #n ")" ::: "memory")
; #define PG8_WAIT_L(n) asm volatile("s_waitcnt lgkmcnt(" #n ")" ::: "memory")
; #define PG8_BAR __builtin_amdgcn_s_barrier()
; #define PG8_SCHED __builtin_amdgcn_sched_barrier(0)
; template <class Epi, class Sched, bool ALIGN_EPI = false, bool SP2 = false>
; __device__ __forceinline__ void gemm_phase(PG8_LAS unsigned char* lds, const Gemm g, const Sched& S, const Epi& E, const int wave_id) {
;     ...
;             PG8_LDA(At, 1, 1); PG8_STAGE(PG8_SB(1, 0), b3, voffB); PG8_STAGE(PG8_SB(1, 1), b3 + hstepB, voffB); PG8_STAGE(PG8_SA(1, 0), a3, voffA);
;             PG8_WAIT_V(8); PG8_WAIT_L(0); PG8_BAR; PG8_MMA(1, 0, At, B0); PG8_MMA(1, 1, At, B1); PG8_BAR; PG8_SCHED;
;     ...
;         if constexpr (ALIGN_EPI) { if (wr == 0) PG8_BAR; }
	s_add_i32 s12, s39, s35
	v_lshl_add_u64 v[222:223], v[222:223], 0, s[62:63]
	s_mov_b32 m0, s12
	ds_read_b128 v[182:185], v212 offset:49152
	ds_read_b128 v[186:189], v212 offset:50176
	ds_read_b128 v[190:193], v212 offset:51200
	ds_read_b128 v[194:197], v212 offset:52224
	ds_read_b128 v[198:201], v212 offset:53248
	ds_read_b128 v[202:205], v212 offset:54272
	ds_read_b128 v[214:217], v212 offset:55296
	ds_read_b128 v[218:221], v212 offset:56320
	global_load_lds_dwordx4 v[222:223], off
	s_add_i32 m0, s12, 0x2000
	s_add_u32 s12, s28, 0x80080
	v_lshl_add_u64 v[222:223], v[224:225], 0, s[62:63]
	s_addc_u32 s13, s29, 0
	s_add_i32 s28, vcc_hi, s35
	global_load_lds_dwordx4 v[222:223], off
	v_lshl_add_u64 v[222:223], s[12:13], 0, v[164:165]
	s_mov_b32 m0, s28
	s_nop 0
	global_load_lds_dwordx4 v[222:223], off
	v_lshl_add_u64 v[222:223], s[12:13], 0, v[168:169]
	s_add_i32 m0, s28, 0x2000
	s_nop 0
	global_load_lds_dwordx4 v[222:223], off
	v_lshl_add_u64 v[222:223], v[234:235], 0, s[62:63]
	s_mov_b32 m0, s80
	s_nop 0
	global_load_lds_dwordx4 v[222:223], off
	v_lshl_add_u64 v[222:223], v[236:237], 0, s[62:63]
	s_mov_b32 m0, s81
	s_nop 0
	global_load_lds_dwordx4 v[222:223], off
	s_waitcnt vmcnt(8)
	s_waitcnt lgkmcnt(0)
	s_barrier
	s_setprio 1
	s_waitcnt lgkmcnt(0)
	v_mfma_f32_16x16x32_bf16 v[62:65], v[122:125], v[182:185], v[62:65]
	v_mfma_f32_16x16x32_bf16 v[58:61], v[138:141], v[182:185], v[58:61]
	v_mfma_f32_16x16x32_bf16 v[46:49], v[122:125], v[190:193], v[46:49]
	v_mfma_f32_16x16x32_bf16 v[42:45], v[138:141], v[190:193], v[42:45]
	v_mfma_f32_16x16x32_bf16 v[30:33], v[122:125], v[198:201], v[30:33]
	v_mfma_f32_16x16x32_bf16 v[26:29], v[138:141], v[198:201], v[26:29]
	v_mfma_f32_16x16x32_bf16 v[14:17], v[122:125], v[214:217], v[14:17]
	v_mfma_f32_16x16x32_bf16 v[10:13], v[138:141], v[214:217], v[10:13]
	v_mfma_f32_16x16x32_bf16 v[62:65], v[134:137], v[186:189], v[62:65]
	v_mfma_f32_16x16x32_bf16 v[58:61], v[142:145], v[186:189], v[58:61]
	v_mfma_f32_16x16x32_bf16 v[46:49], v[134:137], v[194:197], v[46:49]
	v_mfma_f32_16x16x32_bf16 v[42:45], v[142:145], v[194:197], v[42:45]
	v_mfma_f32_16x16x32_bf16 v[30:33], v[134:137], v[202:205], v[30:33]
	v_mfma_f32_16x16x32_bf16 v[26:29], v[142:145], v[202:205], v[26:29]
	v_mfma_f32_16x16x32_bf16 v[14:17], v[134:137], v[218:221], v[14:17]
	v_mfma_f32_16x16x32_bf16 v[10:13], v[142:145], v[218:221], v[10:13]
	s_setprio 0
	s_setprio 1
	v_mfma_f32_16x16x32_bf16 v[54:57], v[146:149], v[182:185], v[54:57]
	v_mfma_f32_16x16x32_bf16 v[50:53], v[154:157], v[182:185], v[50:53]
	v_mfma_f32_16x16x32_bf16 v[38:41], v[146:149], v[190:193], v[38:41]
	v_mfma_f32_16x16x32_bf16 v[34:37], v[154:157], v[190:193], v[34:37]
	v_mfma_f32_16x16x32_bf16 v[22:25], v[146:149], v[198:201], v[22:25]
	v_mfma_f32_16x16x32_bf16 v[18:21], v[154:157], v[198:201], v[18:21]
	v_mfma_f32_16x16x32_bf16 v[6:9], v[146:149], v[214:217], v[6:9]
	v_mfma_f32_16x16x32_bf16 v[2:5], v[154:157], v[214:217], v[2:5]
	v_mfma_f32_16x16x32_bf16 v[54:57], v[150:153], v[186:189], v[54:57]
	v_mfma_f32_16x16x32_bf16 v[50:53], v[158:161], v[186:189], v[50:53]
	v_mfma_f32_16x16x32_bf16 v[38:41], v[150:153], v[194:197], v[38:41]
	v_mfma_f32_16x16x32_bf16 v[34:37], v[158:161], v[194:197], v[34:37]
	v_mfma_f32_16x16x32_bf16 v[22:25], v[150:153], v[202:205], v[22:25]
	v_mfma_f32_16x16x32_bf16 v[18:21], v[158:161], v[202:205], v[18:21]
	v_mfma_f32_16x16x32_bf16 v[6:9], v[150:153], v[218:221], v[6:9]
	v_mfma_f32_16x16x32_bf16 v[2:5], v[158:161], v[218:221], v[2:5]
	s_setprio 0
	s_barrier
	s_add_i32 vcc_lo, vcc_lo, 2
	s_add_u32 s38, s38, 0x100
	s_addc_u32 s91, s91, 0
	s_cmp_gt_u32 vcc_lo, 29
	s_mov_b64 s[12:13], s[10:11]
	s_cbranch_scc0 .LBB0_189
	s_and_b64 vcc, exec, s[20:21]
	s_cbranch_vccz .LBB0_192
	s_barrier

; #define PG8_BAR __builtin_amdgcn_s_barrier()
; template <class Epi, class Sched, bool ALIGN_EPI = false, bool SP2 = false>
; __device__ __forceinline__ void gemm_phase(PG8_LAS unsigned char* lds, const Gemm g, const Sched& S, const Epi& E, const int wave_id) {
;     ...
;         if (!has_next) break;
; #pragma unroll
;         for (int a = 0; a < 2; ++a)
; #pragma unroll
;             for (int b = 0; b < 2; ++b)
; #pragma unroll
;                 for (int m = 0; m < 4; ++m)
; #pragma unroll
;                     for (int n = 0; n < 2; ++n) acc[a][b][m][n] = (f32x4){0.f, 0.f, 0.f, 0.f};
;         cur = nxt; cA = nA; cB = nB; ++ui;
;         if constexpr (Epi::HAS_PF) E.prefetch(cur, tid);
;         if constexpr (ALIGN_EPI) { if (wr == 1) PG8_BAR; }
.LBB0_280:
	s_or_b64 exec, exec, s[10:11]
	s_and_b64 vcc, exec, s[8:9]
	s_mov_b64 s[8:9], -1
	s_cbranch_vccnz .LBB0_183
	s_mov_b32 s98, 1
	s_andn2_b64 vcc, exec, s[18:19]
	s_cbranch_vccnz .LBB0_182
	s_barrier
	s_branch .LBB0_182

; #define PG8_STAGE(bufoff, gbase, voff) do { _Pragma("unroll") for (int _i = 0; _i < 2; ++_i) \
;         __builtin_amdgcn_global_load_lds((const unsigned*)((const char*)(gbase) + (voff)[_i]), (PG8_LAS unsigned*)(lds + (bufoff) + ldsw + _i * 8192), 16, 0, 0); } while (0)
; #define PG8_LDA(dst, b, h) do { _Pragma("unroll") for (int m = 0; m < 4; ++m) _Pragma("unroll") for (int k = 0; k < 2; ++k) dst[m][k] = *(const PG8_LAS bf16x8*)(lds + PG8_SA(b, h) + aoff + m * 2048 + k * 1024); } while (0)
; #define PG8_LDB(dst, b, h) do { _Pragma("unroll") for (int n = 0; n < 2; ++n) _Pragma("unroll") for (int k = 0; k < 2; ++k) dst[n][k] = *(const PG8_LAS bf16x8*)(lds + PG8_SB(b, h) + boff + n * 2048 + k * 1024); } while (0)
; #define PG8_MMA(ai, bj, At, Bt) do { __builtin_amdgcn_s_setprio(1); _Pragma("unroll") for (int m = 0; m < 4; ++m) _Pragma("unroll") for (int n = 0; n < 2; ++n) _Pragma("unroll") for (int k = 0; k < 2; ++k) \
;         acc[ai][bj][m][n] = __builtin_amdgcn_mfma_f32_16x16x32_bf16(Bt[n][k], At[m][k], acc[ai][bj][m][n], 0, 0, 0); __builtin_amdgcn_s_setprio(0); } while (0)
; #define PG8_WAIT_V(n) asm volatile("s_waitcnt vmcnt(" #n ")" ::: "memory")
; #define PG8_WAIT_L(n) asm volatile("s_waitcnt lgkmcnt(" #n ")" ::: "memory")
; #define PG8_BAR __builtin_amdgcn_s_barrier()
; template <class Epi, class Sched, bool ALIGN_EPI = false, bool SP2 = false>
; __device__ __forceinline__ void gemm_phase(PG8_LAS unsigned char* lds, const Gemm g, const Sched& S, const Epi& E, const int wave_id) {
;     ...
;             const char* a1 = cA + (size_t)(t + 1) * kstep;
;             const char* a2 = last ? nA : cA + (size_t)(t + 2) * kstep; const char* b2 = last ? nB : cB + (size_t)(t + 2) * kstep;
;             const char* a3 = a2 + kstep; const char* b3 = b2 + kstep;
;             if (last && has_next) S.a_ready(nxt);
;             if constexpr (SP2) {
;             PG8_LDB(B0, 0, 0); PG8_LDB(B1, 0, 1); PG8_SCHED; PG8_LDA(At, 0, 0); PG8_STAGE(PG8_SA(1, 1), a1 + hstepA, voffA);
;             PG8_WAIT_V(8); PG8_WAIT_L(0); PG8_BAR; PG8_MMA(0, 0, At, B0); PG8_MMA(0, 1, At, B1); PG8_BAR; PG8_SCHED;
;             PG8_LDA(At, 0, 1); PG8_STAGE(PG8_SB(0, 0), b2, voffB); PG8_STAGE(PG8_SB(0, 1), b2 + hstepB, voffB); PG8_STAGE(PG8_SA(0, 0), a2, voffA);
;             PG8_WAIT_V(8); PG8_WAIT_L(0); PG8_BAR; PG8_MMA(1, 0, At, B0); PG8_MMA(1, 1, At, B1); PG8_BAR; PG8_SCHED;
.LBB0_297:
	s_add_u32 s12, s10, 0xfffc0080
	s_addc_u32 s13, s11, -1
	s_add_i32 s20, 0, 0x10000
	s_cmp_eq_u32 vcc_lo, 12
	s_cselect_b32 s35, s15, s13
	s_cselect_b32 s34, s27, s12
	v_add_u32_e32 v0, s20, v206
	s_cselect_b32 s13, s25, s38
	s_cselect_b32 s12, s36, s37
	s_add_i32 vcc_hi, 0, 0x14000
	ds_read_b128 v[122:125], v0
	ds_read_b128 v[134:137], v0 offset:1024
	ds_read_b128 v[138:141], v0 offset:2048
	ds_read_b128 v[142:145], v0 offset:3072
	v_add_u32_e32 v0, vcc_hi, v206
	ds_read_b128 v[146:149], v0
	ds_read_b128 v[150:153], v0 offset:1024
	ds_read_b128 v[154:157], v0 offset:2048
	ds_read_b128 v[158:161], v0 offset:3072
	v_lshl_add_u64 v[222:223], s[10:11], 0, v[178:179]
	s_add_i32 m0, s17, 0xc000
	ds_read_b128 v[182:185], v212
	ds_read_b128 v[186:189], v212 offset:1024
	ds_read_b128 v[190:193], v212 offset:2048
	ds_read_b128 v[194:197], v212 offset:3072
	ds_read_b128 v[198:201], v212 offset:4096
	ds_read_b128 v[202:205], v212 offset:5120
	ds_read_b128 v[214:217], v212 offset:6144
	ds_read_b128 v[218:221], v212 offset:7168
	global_load_lds_dwordx4 v[222:223], off
	v_lshl_add_u64 v[222:223], s[10:11], 0, v[180:181]
	s_add_i32 m0, s17, 0xe000
	s_nop 0
	global_load_lds_dwordx4 v[222:223], off
	s_waitcnt vmcnt(24)
	s_cmp_eq_u32 s98, 1
	s_cbranch_scc1 .Lrw_11
	s_waitcnt vmcnt(8)
.Lrw_11:
	s_waitcnt lgkmcnt(0)
	s_barrier
	s_setprio 1
	s_waitcnt lgkmcnt(0)
	v_mfma_f32_16x16x32_bf16 v[130:133], v[122:125], v[182:185], v[130:133]
	v_mfma_f32_16x16x32_bf16 v[126:129], v[138:141], v[182:185], v[126:129]
	v_mfma_f32_16x16x32_bf16 v[110:113], v[122:125], v[190:193], v[110:113]
	v_mfma_f32_16x16x32_bf16 v[106:109], v[138:141], v[190:193], v[106:109]
	v_mfma_f32_16x16x32_bf16 v[94:97], v[122:125], v[198:201], v[94:97]
	v_mfma_f32_16x16x32_bf16 v[90:93], v[138:141], v[198:201], v[90:93]
	v_mfma_f32_16x16x32_bf16 v[78:81], v[122:125], v[214:217], v[78:81]
	v_mfma_f32_16x16x32_bf16 v[74:77], v[138:141], v[214:217], v[74:77]
	v_mfma_f32_16x16x32_bf16 v[130:133], v[134:137], v[186:189], v[130:133]
	v_mfma_f32_16x16x32_bf16 v[126:129], v[142:145], v[186:189], v[126:129]
	v_mfma_f32_16x16x32_bf16 v[110:113], v[134:137], v[194:197], v[110:113]
	v_mfma_f32_16x16x32_bf16 v[106:109], v[142:145], v[194:197], v[106:109]
	v_mfma_f32_16x16x32_bf16 v[94:97], v[134:137], v[202:205], v[94:97]
	v_mfma_f32_16x16x32_bf16 v[90:93], v[142:145], v[202:205], v[90:93]
	v_mfma_f32_16x16x32_bf16 v[78:81], v[134:137], v[218:221], v[78:81]
	v_mfma_f32_16x16x32_bf16 v[74:77], v[142:145], v[218:221], v[74:77]
	s_setprio 0
	s_setprio 1
	v_mfma_f32_16x16x32_bf16 v[118:121], v[146:149], v[182:185], v[118:121]
	v_mfma_f32_16x16x32_bf16 v[114:117], v[154:157], v[182:185], v[114:117]
	v_mfma_f32_16x16x32_bf16 v[102:105], v[146:149], v[190:193], v[102:105]
	v_mfma_f32_16x16x32_bf16 v[98:101], v[154:157], v[190:193], v[98:101]
	v_mfma_f32_16x16x32_bf16 v[86:89], v[146:149], v[198:201], v[86:89]
	v_mfma_f32_16x16x32_bf16 v[82:85], v[154:157], v[198:201], v[82:85]
	v_mfma_f32_16x16x32_bf16 v[70:73], v[146:149], v[214:217], v[70:73]
	v_mfma_f32_16x16x32_bf16 v[66:69], v[154:157], v[214:217], v[66:69]
	v_mfma_f32_16x16x32_bf16 v[118:121], v[150:153], v[186:189], v[118:121]
	v_mfma_f32_16x16x32_bf16 v[114:117], v[158:161], v[186:189], v[114:117]
	v_mfma_f32_16x16x32_bf16 v[102:105], v[150:153], v[194:197], v[102:105]
	v_mfma_f32_16x16x32_bf16 v[98:101], v[158:161], v[194:197], v[98:101]
	v_mfma_f32_16x16x32_bf16 v[86:89], v[150:153], v[202:205], v[86:89]
	v_mfma_f32_16x16x32_bf16 v[82:85], v[158:161], v[202:205], v[82:85]
	v_mfma_f32_16x16x32_bf16 v[70:73], v[150:153], v[218:221], v[70:73]
	v_mfma_f32_16x16x32_bf16 v[66:69], v[158:161], v[218:221], v[66:69]
	s_setprio 0
	s_barrier
	s_add_i32 s20, s20, s76
	v_lshl_add_u64 v[222:223], s[12:13], 0, v[164:165]
	s_mov_b32 m0, s20
	ds_read_b128 v[182:185], v212 offset:16384
	ds_read_b128 v[186:189], v212 offset:17408
	ds_read_b128 v[190:193], v212 offset:18432
	ds_read_b128 v[194:197], v212 offset:19456
	ds_read_b128 v[198:201], v212 offset:20480
	ds_read_b128 v[202:205], v212 offset:21504
	ds_read_b128 v[214:217], v212 offset:22528
	ds_read_b128 v[218:221], v212 offset:23552
	global_load_lds_dwordx4 v[222:223], off
	s_add_i32 m0, s20, 0x2000
	s_add_u32 s20, s12, 0x40000
	v_lshl_add_u64 v[224:225], s[12:13], 0, v[168:169]
	s_addc_u32 s21, s13, 0
	s_add_i32 vcc_hi, vcc_hi, s76
	global_load_lds_dwordx4 v[224:225], off
	v_lshl_add_u64 v[234:235], s[20:21], 0, v[164:165]
	s_mov_b32 m0, vcc_hi
	v_lshl_add_u64 v[236:237], s[34:35], 0, v[166:167]
	global_load_lds_dwordx4 v[234:235], off
	v_lshl_add_u64 v[234:235], s[20:21], 0, v[168:169]
	s_add_i32 m0, vcc_hi, 0x2000
	s_nop 0
	global_load_lds_dwordx4 v[234:235], off
	v_lshl_add_u64 v[234:235], s[34:35], 0, v[162:163]
	s_mov_b32 m0, s17
	s_nop 0
	global_load_lds_dwordx4 v[234:235], off
	s_mov_b32 m0, s19
	s_nop 0
	global_load_lds_dwordx4 v[236:237], off
	s_waitcnt vmcnt(24)
	s_cmp_eq_u32 s98, 1
	s_cbranch_scc1 .Lrw_12
	s_waitcnt vmcnt(8)
; #define PG8_STAGE(bufoff, gbase, voff) do { _Pragma("unroll") for (int _i = 0; _i < 2; ++_i) \
;         __builtin_amdgcn_global_load_lds((const unsigned*)((const char*)(gbase) + (voff)[_i]), (PG8_LAS unsigned*)(lds + (bufoff) + ldsw + _i * 8192), 16, 0, 0); } while (0)
; #define PG8_LDA(dst, b, h) do { _Pragma("unroll") for (int m = 0; m < 4; ++m) _Pragma("unroll") for (int k = 0; k < 2; ++k) dst[m][k] = *(const PG8_LAS bf16x8*)(lds + PG8_SA(b, h) + aoff + m * 2048 + k * 1024); } while (0)
; #define PG8_LDB(dst, b, h) do { _Pragma("unroll") for (int n = 0; n < 2; ++n) _Pragma("unroll") for (int k = 0; k < 2; ++k) dst[n][k] = *(const PG8_LAS bf16x8*)(lds + PG8_SB(b, h) + boff + n * 2048 + k * 1024); } while (0)
; #define PG8_MMA(ai, bj, At, Bt) do { __builtin_amdgcn_s_setprio(1); _Pragma("unroll") for (int m = 0; m < 4; ++m) _Pragma("unroll") for (int n = 0; n < 2; ++n) _Pragma("unroll") for (int k = 0; k < 2; ++k) \
;         acc[ai][bj][m][n] = __builtin_amdgcn_mfma_f32_16x16x32_bf16(Bt[n][k], At[m][k], acc[ai][bj][m][n], 0, 0, 0); __builtin_amdgcn_s_setprio(0); } while (0)
; #define PG8_WAIT_V(n) asm volatile("s_waitcnt vmcnt(" #n ")" ::: "memory")
; #define PG8_WAIT_L(n) asm volatile("s_waitcnt lgkmcnt(" #n ")" ::: "memory")
; #define PG8_BAR __builtin_amdgcn_s_barrier()
; #define PG8_SCHED __builtin_amdgcn_sched_barrier(0)
; template <class Epi, class Sched, bool ALIGN_EPI = false, bool SP2 = false>
; __device__ __forceinline__ void gemm_phase(PG8_LAS unsigned char* lds, const Gemm g, const Sched& S, const Epi& E, const int wave_id) {
;     ...
;             PG8_WAIT_V(8); PG8_WAIT_L(0); PG8_BAR; PG8_MMA(1, 0, At, B0); PG8_MMA(1, 1, At, B1); PG8_BAR; PG8_SCHED;
;             PG8_LDB(B0, 1, 0); PG8_LDB(B1, 1, 1); PG8_SCHED; PG8_LDA(At, 1, 0); PG8_STAGE(PG8_SA(0, 1), a2 + hstepA, voffA);
;             PG8_WAIT_V(8); PG8_WAIT_L(0); PG8_BAR; PG8_MMA(0, 0, At, B0); PG8_MMA(0, 1, At, B1); PG8_BAR; PG8_SCHED;
.Lrw_12:
	s_mov_b32 s98, 0
	s_waitcnt lgkmcnt(0)
	s_barrier
	s_setprio 1
	s_waitcnt lgkmcnt(0)
	v_mfma_f32_16x16x32_bf16 v[62:65], v[122:125], v[182:185], v[62:65]
	v_mfma_f32_16x16x32_bf16 v[58:61], v[138:141], v[182:185], v[58:61]
	v_mfma_f32_16x16x32_bf16 v[46:49], v[122:125], v[190:193], v[46:49]
	v_mfma_f32_16x16x32_bf16 v[42:45], v[138:141], v[190:193], v[42:45]
	v_mfma_f32_16x16x32_bf16 v[30:33], v[122:125], v[198:201], v[30:33]
	v_mfma_f32_16x16x32_bf16 v[26:29], v[138:141], v[198:201], v[26:29]
	v_mfma_f32_16x16x32_bf16 v[14:17], v[122:125], v[214:217], v[14:17]
	v_mfma_f32_16x16x32_bf16 v[10:13], v[138:141], v[214:217], v[10:13]
	v_mfma_f32_16x16x32_bf16 v[62:65], v[134:137], v[186:189], v[62:65]
	v_mfma_f32_16x16x32_bf16 v[58:61], v[142:145], v[186:189], v[58:61]
	v_mfma_f32_16x16x32_bf16 v[46:49], v[134:137], v[194:197], v[46:49]
	v_mfma_f32_16x16x32_bf16 v[42:45], v[142:145], v[194:197], v[42:45]
	v_mfma_f32_16x16x32_bf16 v[30:33], v[134:137], v[202:205], v[30:33]
	v_mfma_f32_16x16x32_bf16 v[26:29], v[142:145], v[202:205], v[26:29]
	v_mfma_f32_16x16x32_bf16 v[14:17], v[134:137], v[218:221], v[14:17]
	v_mfma_f32_16x16x32_bf16 v[10:13], v[142:145], v[218:221], v[10:13]
	s_setprio 0
	s_setprio 1
	v_mfma_f32_16x16x32_bf16 v[54:57], v[146:149], v[182:185], v[54:57]
	v_mfma_f32_16x16x32_bf16 v[50:53], v[154:157], v[182:185], v[50:53]
	v_mfma_f32_16x16x32_bf16 v[38:41], v[146:149], v[190:193], v[38:41]
	v_mfma_f32_16x16x32_bf16 v[34:37], v[154:157], v[190:193], v[34:37]
	v_mfma_f32_16x16x32_bf16 v[22:25], v[146:149], v[198:201], v[22:25]
	v_mfma_f32_16x16x32_bf16 v[18:21], v[154:157], v[198:201], v[18:21]
	v_mfma_f32_16x16x32_bf16 v[6:9], v[146:149], v[214:217], v[6:9]
	v_mfma_f32_16x16x32_bf16 v[2:5], v[154:157], v[214:217], v[2:5]
	v_mfma_f32_16x16x32_bf16 v[54:57], v[150:153], v[186:189], v[54:57]
	v_mfma_f32_16x16x32_bf16 v[50:53], v[158:161], v[186:189], v[50:53]
	v_mfma_f32_16x16x32_bf16 v[38:41], v[150:153], v[194:197], v[38:41]
	v_mfma_f32_16x16x32_bf16 v[34:37], v[158:161], v[194:197], v[34:37]
	v_mfma_f32_16x16x32_bf16 v[22:25], v[150:153], v[202:205], v[22:25]
	v_mfma_f32_16x16x32_bf16 v[18:21], v[158:161], v[202:205], v[18:21]
	v_mfma_f32_16x16x32_bf16 v[6:9], v[150:153], v[218:221], v[6:9]
	v_mfma_f32_16x16x32_bf16 v[2:5], v[158:161], v[218:221], v[2:5]
	s_setprio 0
	s_barrier
	s_add_i32 vcc_hi, 0, 0x18000
	v_add_u32_e32 v0, vcc_hi, v206
	s_add_i32 s39, 0, 0x1c000
	ds_read_b128 v[122:125], v0
	ds_read_b128 v[134:137], v0 offset:1024
	ds_read_b128 v[138:141], v0 offset:2048
	ds_read_b128 v[142:145], v0 offset:3072
	v_add_u32_e32 v0, s39, v206
	ds_read_b128 v[146:149], v0
	ds_read_b128 v[150:153], v0 offset:1024
	ds_read_b128 v[154:157], v0 offset:2048
	ds_read_b128 v[158:161], v0 offset:3072
	s_add_u32 s20, s34, 0x40000
	s_addc_u32 s21, s35, 0
	s_mov_b32 m0, s77
	v_lshl_add_u64 v[240:241], s[20:21], 0, v[162:163]
	ds_read_b128 v[182:185], v212 offset:32768
	ds_read_b128 v[186:189], v212 offset:33792
	ds_read_b128 v[190:193], v212 offset:34816
	ds_read_b128 v[194:197], v212 offset:35840
	ds_read_b128 v[198:201], v212 offset:36864
	ds_read_b128 v[202:205], v212 offset:37888
	ds_read_b128 v[214:217], v212 offset:38912
	ds_read_b128 v[218:221], v212 offset:39936
	global_load_lds_dwordx4 v[240:241], off
	v_lshl_add_u64 v[240:241], s[20:21], 0, v[166:167]
	s_mov_b32 m0, s80
	s_nop 0
	global_load_lds_dwordx4 v[240:241], off
	s_waitcnt vmcnt(8)
	s_waitcnt lgkmcnt(0)
	s_barrier
	s_setprio 1
	s_waitcnt lgkmcnt(0)
	v_mfma_f32_16x16x32_bf16 v[130:133], v[122:125], v[182:185], v[130:133]
	v_mfma_f32_16x16x32_bf16 v[126:129], v[138:141], v[182:185], v[126:129]
	v_mfma_f32_16x16x32_bf16 v[110:113], v[122:125], v[190:193], v[110:113]
	v_mfma_f32_16x16x32_bf16 v[106:109], v[138:141], v[190:193], v[106:109]
	v_mfma_f32_16x16x32_bf16 v[94:97], v[122:125], v[198:201], v[94:97]
	v_mfma_f32_16x16x32_bf16 v[90:93], v[138:141], v[198:201], v[90:93]
	v_mfma_f32_16x16x32_bf16 v[78:81], v[122:125], v[214:217], v[78:81]
	v_mfma_f32_16x16x32_bf16 v[74:77], v[138:141], v[214:217], v[74:77]
	v_mfma_f32_16x16x32_bf16 v[130:133], v[134:137], v[186:189], v[130:133]
	v_mfma_f32_16x16x32_bf16 v[126:129], v[142:145], v[186:189], v[126:129]
	v_mfma_f32_16x16x32_bf16 v[110:113], v[134:137], v[194:197], v[110:113]
	v_mfma_f32_16x16x32_bf16 v[106:109], v[142:145], v[194:197], v[106:109]
	v_mfma_f32_16x16x32_bf16 v[94:97], v[134:137], v[202:205], v[94:97]
	v_mfma_f32_16x16x32_bf16 v[90:93], v[142:145], v[202:205], v[90:93]
	v_mfma_f32_16x16x32_bf16 v[78:81], v[134:137], v[218:221], v[78:81]
	v_mfma_f32_16x16x32_bf16 v[74:77], v[142:145], v[218:221], v[74:77]
	s_setprio 0
	s_setprio 1
	v_mfma_f32_16x16x32_bf16 v[118:121], v[146:149], v[182:185], v[118:121]
	v_mfma_f32_16x16x32_bf16 v[114:117], v[154:157], v[182:185], v[114:117]
	v_mfma_f32_16x16x32_bf16 v[102:105], v[146:149], v[190:193], v[102:105]
	v_mfma_f32_16x16x32_bf16 v[98:101], v[154:157], v[190:193], v[98:101]
	v_mfma_f32_16x16x32_bf16 v[86:89], v[146:149], v[198:201], v[86:89]
	v_mfma_f32_16x16x32_bf16 v[82:85], v[154:157], v[198:201], v[82:85]
	v_mfma_f32_16x16x32_bf16 v[70:73], v[146:149], v[214:217], v[70:73]
	v_mfma_f32_16x16x32_bf16 v[66:69], v[154:157], v[214:217], v[66:69]
	v_mfma_f32_16x16x32_bf16 v[118:121], v[150:153], v[186:189], v[118:121]
	v_mfma_f32_16x16x32_bf16 v[114:117], v[158:161], v[186:189], v[114:117]
	v_mfma_f32_16x16x32_bf16 v[102:105], v[150:153], v[194:197], v[102:105]
	v_mfma_f32_16x16x32_bf16 v[98:101], v[158:161], v[194:197], v[98:101]
	v_mfma_f32_16x16x32_bf16 v[86:89], v[150:153], v[202:205], v[86:89]
	v_mfma_f32_16x16x32_bf16 v[82:85], v[158:161], v[202:205], v[82:85]
	v_mfma_f32_16x16x32_bf16 v[70:73], v[150:153], v[218:221], v[70:73]
	v_mfma_f32_16x16x32_bf16 v[66:69], v[158:161], v[218:221], v[66:69]
	s_setprio 0
	s_barrier
; #define PG8_STAGE(bufoff, gbase, voff) do { _Pragma("unroll") for (int _i = 0; _i < 2; ++_i) \
;         __builtin_amdgcn_global_load_lds((const unsigned*)((const char*)(gbase) + (voff)[_i]), (PG8_LAS unsigned*)(lds + (bufoff) + ldsw + _i * 8192), 16, 0, 0); } while (0)
; #define PG8_LDA(dst, b, h) do { _Pragma("unroll") for (int m = 0; m < 4; ++m) _Pragma("unroll") for (int k = 0; k < 2; ++k) dst[m][k] = *(const PG8_LAS bf16x8*)(lds + PG8_SA(b, h) + aoff + m * 2048 + k * 1024); } while (0)
; #define PG8_MMA(ai, bj, At, Bt) do { __builtin_amdgcn_s_setprio(1); _Pragma("unroll") for (int m = 0; m < 4; ++m) _Pragma("unroll") for (int n = 0; n < 2; ++n) _Pragma("unroll") for (int k = 0; k < 2; ++k) \
;         acc[ai][bj][m][n] = __builtin_amdgcn_mfma_f32_16x16x32_bf16(Bt[n][k], At[m][k], acc[ai][bj][m][n], 0, 0, 0); __builtin_amdgcn_s_setprio(0); } while (0)
; #define PG8_WAIT_V(n) asm volatile("s_waitcnt vmcnt(" #n ")" ::: "memory")
; #define PG8_WAIT_L(n) asm volatile("s_waitcnt lgkmcnt(" #n ")" ::: "memory")
; #define PG8_BAR __builtin_amdgcn_s_barrier()
; #define PG8_SCHED __builtin_amdgcn_sched_barrier(0)
; template <class Epi, class Sched, bool ALIGN_EPI = false, bool SP2 = false>
; __device__ __forceinline__ void gemm_phase(PG8_LAS unsigned char* lds, const Gemm g, const Sched& S, const Epi& E, const int wave_id) {
;     ...
;             PG8_LDA(At, 1, 1); PG8_STAGE(PG8_SB(1, 0), b3, voffB); PG8_STAGE(PG8_SB(1, 1), b3 + hstepB, voffB); PG8_STAGE(PG8_SA(1, 0), a3, voffA);
;             PG8_WAIT_V(8); PG8_WAIT_L(0); PG8_BAR; PG8_MMA(1, 0, At, B0); PG8_MMA(1, 1, At, B1); PG8_BAR; PG8_SCHED;
;     ...
;         if constexpr (ALIGN_EPI) { if (wr == 0) PG8_BAR; }
	s_add_i32 s20, vcc_hi, s76
	v_lshl_add_u64 v[222:223], v[222:223], 0, s[62:63]
	s_mov_b32 m0, s20
	ds_read_b128 v[182:185], v212 offset:49152
	ds_read_b128 v[186:189], v212 offset:50176
	ds_read_b128 v[190:193], v212 offset:51200
	ds_read_b128 v[194:197], v212 offset:52224
	ds_read_b128 v[198:201], v212 offset:53248
	ds_read_b128 v[202:205], v212 offset:54272
	ds_read_b128 v[214:217], v212 offset:55296
	ds_read_b128 v[218:221], v212 offset:56320
	global_load_lds_dwordx4 v[222:223], off
	s_add_i32 m0, s20, 0x2000
	s_add_u32 s12, s12, 0x40080
	v_lshl_add_u64 v[222:223], v[224:225], 0, s[62:63]
	s_addc_u32 s13, s13, 0
	s_add_i32 s20, s39, s76
	global_load_lds_dwordx4 v[222:223], off
	v_lshl_add_u64 v[222:223], s[12:13], 0, v[164:165]
	s_mov_b32 m0, s20
	s_nop 0
	global_load_lds_dwordx4 v[222:223], off
	v_lshl_add_u64 v[222:223], s[12:13], 0, v[168:169]
	s_add_i32 m0, s20, 0x2000
	s_nop 0
	global_load_lds_dwordx4 v[222:223], off
	v_lshl_add_u64 v[222:223], v[234:235], 0, s[62:63]
	s_mov_b32 m0, s82
	s_nop 0
	global_load_lds_dwordx4 v[222:223], off
	v_lshl_add_u64 v[222:223], v[236:237], 0, s[62:63]
	s_mov_b32 m0, s83
	s_nop 0
	global_load_lds_dwordx4 v[222:223], off
	s_waitcnt vmcnt(8)
	s_waitcnt lgkmcnt(0)
	s_barrier
	s_setprio 1
	s_waitcnt lgkmcnt(0)
	v_mfma_f32_16x16x32_bf16 v[62:65], v[122:125], v[182:185], v[62:65]
	v_mfma_f32_16x16x32_bf16 v[58:61], v[138:141], v[182:185], v[58:61]
	v_mfma_f32_16x16x32_bf16 v[46:49], v[122:125], v[190:193], v[46:49]
	v_mfma_f32_16x16x32_bf16 v[42:45], v[138:141], v[190:193], v[42:45]
	v_mfma_f32_16x16x32_bf16 v[30:33], v[122:125], v[198:201], v[30:33]
	v_mfma_f32_16x16x32_bf16 v[26:29], v[138:141], v[198:201], v[26:29]
	v_mfma_f32_16x16x32_bf16 v[14:17], v[122:125], v[214:217], v[14:17]
	v_mfma_f32_16x16x32_bf16 v[10:13], v[138:141], v[214:217], v[10:13]
	v_mfma_f32_16x16x32_bf16 v[62:65], v[134:137], v[186:189], v[62:65]
	v_mfma_f32_16x16x32_bf16 v[58:61], v[142:145], v[186:189], v[58:61]
	v_mfma_f32_16x16x32_bf16 v[46:49], v[134:137], v[194:197], v[46:49]
	v_mfma_f32_16x16x32_bf16 v[42:45], v[142:145], v[194:197], v[42:45]
	v_mfma_f32_16x16x32_bf16 v[30:33], v[134:137], v[202:205], v[30:33]
	v_mfma_f32_16x16x32_bf16 v[26:29], v[142:145], v[202:205], v[26:29]
	v_mfma_f32_16x16x32_bf16 v[14:17], v[134:137], v[218:221], v[14:17]
	v_mfma_f32_16x16x32_bf16 v[10:13], v[142:145], v[218:221], v[10:13]
	s_setprio 0
	s_setprio 1
	v_mfma_f32_16x16x32_bf16 v[54:57], v[146:149], v[182:185], v[54:57]
	v_mfma_f32_16x16x32_bf16 v[50:53], v[154:157], v[182:185], v[50:53]
	v_mfma_f32_16x16x32_bf16 v[38:41], v[146:149], v[190:193], v[38:41]
	v_mfma_f32_16x16x32_bf16 v[34:37], v[154:157], v[190:193], v[34:37]
	v_mfma_f32_16x16x32_bf16 v[22:25], v[146:149], v[198:201], v[22:25]
	v_mfma_f32_16x16x32_bf16 v[18:21], v[154:157], v[198:201], v[18:21]
	v_mfma_f32_16x16x32_bf16 v[6:9], v[146:149], v[214:217], v[6:9]
	v_mfma_f32_16x16x32_bf16 v[2:5], v[154:157], v[214:217], v[2:5]
	v_mfma_f32_16x16x32_bf16 v[54:57], v[150:153], v[186:189], v[54:57]
	v_mfma_f32_16x16x32_bf16 v[50:53], v[158:161], v[186:189], v[50:53]
	v_mfma_f32_16x16x32_bf16 v[38:41], v[150:153], v[194:197], v[38:41]
	v_mfma_f32_16x16x32_bf16 v[34:37], v[158:161], v[194:197], v[34:37]
	v_mfma_f32_16x16x32_bf16 v[22:25], v[150:153], v[202:205], v[22:25]
	v_mfma_f32_16x16x32_bf16 v[18:21], v[158:161], v[202:205], v[18:21]
	v_mfma_f32_16x16x32_bf16 v[6:9], v[150:153], v[218:221], v[6:9]
	v_mfma_f32_16x16x32_bf16 v[2:5], v[158:161], v[218:221], v[2:5]
	s_setprio 0
	s_barrier
	s_add_i32 vcc_lo, vcc_lo, 2
	s_add_u32 s10, s10, 0x100
	s_addc_u32 s11, s11, 0
	s_add_u32 s37, s37, 0x100
	s_addc_u32 s38, s38, 0
	s_cmp_gt_u32 vcc_lo, 13
	s_cbranch_scc0 .LBB0_297
	s_and_b64 vcc, exec, s[22:23]
	s_cbranch_vccz .LBB0_300
	s_barrier

; #define PG8_BAR __builtin_amdgcn_s_barrier()
; template <class Epi, class Sched, bool ALIGN_EPI = false, bool SP2 = false>
; __device__ __forceinline__ void gemm_phase(PG8_LAS unsigned char* lds, const Gemm g, const Sched& S, const Epi& E, const int wave_id) {
;     ...
;         if (!has_next) break;
; #pragma unroll
;         for (int a = 0; a < 2; ++a)
; #pragma unroll
;             for (int b = 0; b < 2; ++b)
; #pragma unroll
;                 for (int m = 0; m < 4; ++m)
; #pragma unroll
;                     for (int n = 0; n < 2; ++n) acc[a][b][m][n] = (f32x4){0.f, 0.f, 0.f, 0.f};
;         cur = nxt; cA = nA; cB = nB; ++ui;
;         if constexpr (Epi::HAS_PF) E.prefetch(cur, tid);
;         if constexpr (ALIGN_EPI) { if (wr == 1) PG8_BAR; }
.LBB0_388:
	s_or_b64 exec, exec, s[10:11]
	s_andn2_b64 vcc, exec, s[8:9]
	s_mov_b64 s[8:9], -1
	s_cbranch_vccnz .LBB0_293
	s_mov_b32 s98, 1
	v_readlane_b32 s8, v254, 62
	v_readlane_b32 s9, v254, 63
	s_andn2_b64 vcc, exec, s[8:9]
	s_cbranch_vccnz .LBB0_292
	s_barrier
	s_branch .LBB0_292
